# P2: XCD-aware tile order (8x4 tile patches per XCD) for L2 reuse of A
# speedup vs baseline: 1.0124x; 1.0124x over previous
.LBB0_465:
	s_cmpk_lg_i32 s11, 0x100
	s_cbranch_scc1 .Ltile_orig_P2
	s_and_b32 s100, s20, 7
	s_lshr_b32 s101, s20, 8
	s_lshl_b32 s101, s101, 3
	s_add_i32 s100, s100, s101
	s_bfe_u32 s101, s20, 0x50003
	s_cmp_lt_u32 s100, 45
	s_cbranch_scc0 .Ltile_lin_P2
	s_mul_i32 s4, s100, 0x1c72
	s_lshr_b32 s4, s4, 16
	s_mul_i32 s6, s4, 9
	s_sub_i32 s6, s100, s6
	s_lshl_b32 s6, s6, 3
	s_and_b32 m0, s101, 7
	s_add_i32 s6, s6, m0
	s_lshl_b32 s4, s4, 2
	s_lshr_b32 m0, s101, 3
	s_add_i32 s4, s4, m0
	s_branch .Ltile_dec_P2
.Ltile_lin_P2:
	s_sub_i32 s100, s100, 45
	s_lshl_b32 s100, s100, 5
	s_add_i32 s100, s100, s101
	s_addk_i32 s100, 1440
	s_mul_hi_i32 s4, s100, 0x38e38e39
	s_lshr_b32 s6, s4, 31
	s_ashr_i32 s4, s4, 4
	s_add_i32 s4, s4, s6
	s_mul_i32 s6, s4, 0x48
	s_sub_i32 s6, s100, s6
	s_branch .Ltile_dec_P2

.Ltile_dec_P2:
	s_lshl_b32 s6, s6, 8
	v_add_u32_e32 v2, s6, v204
	v_ashrrev_i32_e32 v3, 31, v2
	v_lshlrev_b64 v[2:3], 11, v[2:3]
	v_lshl_add_u64 v[168:169], v[162:163], 0, v[2:3]
	v_add_co_u32_e32 v56, vcc, s34, v168
	s_lshl_b32 s7, s4, 8
	s_nop 0
	v_addc_co_u32_e32 v57, vcc, 0, v169, vcc
	v_add_u32_e32 v2, s7, v204
	s_waitcnt vmcnt(9)
	v_add_co_u32_e32 v58, vcc, s35, v168
	v_ashrrev_i32_e32 v3, 31, v2
	s_nop 0
	v_addc_co_u32_e32 v59, vcc, 0, v169, vcc
	v_lshlrev_b64 v[2:3], 11, v[2:3]
	v_add_co_u32_e32 v60, vcc, s36, v168
	v_lshl_add_u64 v[170:171], v[164:165], 0, v[2:3]
	s_nop 0
	v_addc_co_u32_e32 v61, vcc, 0, v169, vcc
	s_waitcnt vmcnt(8)
	v_add_co_u32_e32 v62, vcc, s35, v170
	global_load_dwordx4 v[24:27], v[56:57], off
	global_load_dwordx4 v[28:31], v[58:59], off
	v_addc_co_u32_e32 v63, vcc, 0, v171, vcc
	v_add_co_u32_e32 v64, vcc, s36, v170
	global_load_dwordx4 v[32:35], v[168:169], off
	global_load_dwordx4 v[36:39], v[170:171], off
	v_addc_co_u32_e32 v65, vcc, 0, v171, vcc
	v_add_co_u32_e32 v66, vcc, s34, v170
	global_load_dwordx4 v[40:43], v[62:63], off
	global_load_dwordx4 v[44:47], v[64:65], off
	v_addc_co_u32_e32 v67, vcc, 0, v171, vcc
	global_load_dwordx4 v[48:51], v[60:61], off
	global_load_dwordx4 v[52:55], v[66:67], off
	s_barrier
	global_load_dwordx4 v[114:117], v[168:169], off offset:128
	global_load_dwordx4 v[106:109], v[56:57], off offset:128
	global_load_dwordx4 v[110:113], v[58:59], off offset:128
	global_load_dwordx4 v[126:129], v[60:61], off offset:128
	global_load_dwordx4 v[122:125], v[170:171], off offset:128
	global_load_dwordx4 v[118:121], v[66:67], off offset:128
	global_load_dwordx4 v[134:137], v[62:63], off offset:128
	global_load_dwordx4 v[130:133], v[64:65], off offset:128
	v_readfirstlane_b32 vcc_lo, v168
	v_readfirstlane_b32 vcc_hi, v169
	v_readfirstlane_b32 s100, v170
	v_readfirstlane_b32 s101, v171
	s_nop 1
	v_subrev_u32_e32 v168, vcc_lo, v168
	v_subrev_u32_e32 v170, s100, v170
	v_mov_b32_e32 v2, 0
	s_mov_b32 s4, 0
	v_mov_b32_e32 v3, v2
	v_mov_b32_e32 v4, v2
	v_mov_b32_e32 v5, v2
	v_mov_b32_e32 v6, v2
	v_mov_b32_e32 v7, v2
	v_mov_b32_e32 v8, v2
	v_mov_b32_e32 v9, v2
	v_mov_b32_e32 v10, v2
	v_mov_b32_e32 v11, v2
	v_mov_b32_e32 v12, v2
	v_mov_b32_e32 v13, v2
	v_mov_b32_e32 v14, v2
	v_mov_b32_e32 v15, v2
	v_mov_b32_e32 v16, v2
	v_mov_b32_e32 v17, v2
	v_mov_b32_e32 v18, v2
	v_mov_b32_e32 v19, v2
	v_mov_b32_e32 v20, v2
	v_mov_b32_e32 v21, v2
	v_mov_b32_e32 v22, v2
	v_mov_b32_e32 v23, v2
	v_mov_b32_e32 v56, v2
	v_mov_b32_e32 v57, v2
	v_mov_b32_e32 v58, v2
	v_mov_b32_e32 v59, v2
	v_mov_b32_e32 v60, v2
	v_mov_b32_e32 v61, v2
	v_mov_b32_e32 v62, v2
	v_mov_b32_e32 v63, v2
	v_mov_b32_e32 v64, v2
	v_mov_b32_e32 v65, v2
	v_mov_b32_e32 v66, v2
	v_mov_b32_e32 v67, v2
	v_mov_b32_e32 v68, v2
	v_mov_b32_e32 v69, v2
	v_mov_b32_e32 v70, v2
	v_mov_b32_e32 v71, v2
	v_mov_b32_e32 v72, v2
	v_mov_b32_e32 v73, v2
	v_mov_b32_e32 v74, v2
	v_mov_b32_e32 v75, v2
	v_mov_b32_e32 v76, v2
	v_mov_b32_e32 v77, v2
	v_mov_b32_e32 v78, v2
	v_mov_b32_e32 v79, v2
	v_mov_b32_e32 v80, v2
	v_mov_b32_e32 v81, v2
	v_mov_b32_e32 v82, v2
	v_mov_b32_e32 v83, v2
	v_mov_b32_e32 v84, v2
	v_mov_b32_e32 v85, v2
	s_waitcnt vmcnt(11)
	ds_write_b128 v166, v[40:43] offset:49152
	s_waitcnt vmcnt(10)
	ds_write_b128 v166, v[44:47] offset:57344
	ds_write_b128 v166, v[32:35]
	ds_write_b128 v166, v[36:39] offset:32768
	ds_write_b128 v166, v[24:27] offset:8192
	ds_write_b128 v166, v[28:31] offset:16384
	s_waitcnt vmcnt(9)
	ds_write_b128 v166, v[48:51] offset:24576
	s_waitcnt vmcnt(8)
	ds_write_b128 v166, v[52:55] offset:40960
	v_mov_b32_e32 v24, v2
	v_mov_b32_e32 v25, v2
	v_mov_b32_e32 v26, v2
	v_mov_b32_e32 v27, v2
	v_mov_b32_e32 v28, v2
	v_mov_b32_e32 v29, v2
	v_mov_b32_e32 v30, v2
	v_mov_b32_e32 v31, v2
	v_mov_b32_e32 v32, v2
	v_mov_b32_e32 v33, v2
	v_mov_b32_e32 v34, v2
	v_mov_b32_e32 v35, v2
	v_mov_b32_e32 v36, v2
	v_mov_b32_e32 v37, v2
	v_mov_b32_e32 v38, v2
	v_mov_b32_e32 v39, v2
	v_mov_b32_e32 v40, v2
	v_mov_b32_e32 v41, v2
	v_mov_b32_e32 v42, v2
	v_mov_b32_e32 v43, v2
	v_mov_b32_e32 v44, v2
	v_mov_b32_e32 v45, v2
	v_mov_b32_e32 v46, v2
	v_mov_b32_e32 v47, v2
	v_mov_b32_e32 v48, v2
	v_mov_b32_e32 v49, v2
	v_mov_b32_e32 v50, v2
	v_mov_b32_e32 v51, v2
	v_mov_b32_e32 v52, v2
	v_mov_b32_e32 v53, v2
	v_mov_b32_e32 v54, v2
	v_mov_b32_e32 v55, v2
	v_mov_b32_e32 v86, v2
	v_mov_b32_e32 v87, v2
	v_mov_b32_e32 v88, v2
	v_mov_b32_e32 v89, v2
	v_mov_b32_e32 v90, v2
	v_mov_b32_e32 v91, v2
	v_mov_b32_e32 v92, v2
	v_mov_b32_e32 v93, v2
	v_mov_b32_e32 v94, v2
	v_mov_b32_e32 v95, v2
	v_mov_b32_e32 v96, v2
	v_mov_b32_e32 v97, v2
	v_mov_b32_e32 v98, v2
	v_mov_b32_e32 v99, v2
	v_mov_b32_e32 v100, v2
	v_mov_b32_e32 v101, v2
	v_mov_b32_e32 v102, v2
	v_mov_b32_e32 v103, v2
	v_mov_b32_e32 v104, v2
	v_mov_b32_e32 v105, v2
	v_mov_b32_e32 v138, v2
	v_mov_b32_e32 v139, v2
	v_mov_b32_e32 v140, v2
	v_mov_b32_e32 v141, v2
	v_mov_b32_e32 v142, v2
	v_mov_b32_e32 v143, v2
	v_mov_b32_e32 v144, v2
	v_mov_b32_e32 v145, v2
	v_mov_b32_e32 v146, v2
	v_mov_b32_e32 v147, v2
	v_mov_b32_e32 v148, v2
	v_mov_b32_e32 v149, v2
	v_mov_b32_e32 v150, v2
	v_mov_b32_e32 v151, v2
	v_mov_b32_e32 v152, v2
	v_mov_b32_e32 v153, v2
	v_mov_b32_e32 v154, v2
	v_mov_b32_e32 v155, v2
	v_mov_b32_e32 v156, v2
	v_mov_b32_e32 v157, v2
	v_mov_b32_e32 v158, v2
	v_mov_b32_e32 v159, v2
	v_mov_b32_e32 v160, v2
	v_mov_b32_e32 v161, v2
	s_waitcnt lgkmcnt(0)
	s_barrier
